# v12 + NSA tile-loop back-edge rotation (descriptor decode, type switch, init fill moved before the per-tile barrier)
# baseline (speedup 1.0000x reference)
; #define LAS __attribute__((address_space(3)))
; #define CMP_LOADB(dst, ll_) do { _Pragma("unroll") for (int ks = 0; ks < 2; ++ks) _Pragma("unroll") for (int ct = 0; ct < 2; ++ct) dst[ks][ct] = *(const bf16x8*)(W1T + (size_t)(32 * w + 16 * ct + fr) * 2048 + (ll_) * 64 + ks * 32 + fq * 8); } while (0)
; DI void nsa_compress_item(KA a, const int l, LAS unsigned char* lds, const int it) {
;     ...
;     const int kv = it & 1, ctile = (it >> 1) & 1, bg = it >> 2, b = bg >> 1, g = bg & 1;
;     unsigned char* ws = a->ws; const bf16* H = (const bf16*)(ws + WS_H); const float* ctab = (const float*)(ws + WS_COS); const float* stab = (const float*)(ws + WS_SIN);
;     LAS bf16* At = (LAS bf16*)lds; LAS bf16* Hd = At + 64 * PA;
;     const bf16* W1T = (const bf16*)(ws + WS_WC1 + (size_t)(l * 2 + kv) * MiB);
;     const bf16* W2T = (const bf16*)(ws + WS_SMALL + l * SMALL_STRIDE + (kv ? SM_WV2T : SM_WK2T));
;     const float* pos = a->in[kv ? I_POSV : I_POSK] + l * 32 * 64;
;     const int colbase = (kv ? C_NVC : C_NKC) + g * 64;
;     f32x4 acc[4][2];
; #pragma unroll
;     for (int rt = 0; rt < 4; ++rt) { acc[rt][0] = ZERO4; acc[rt][1] = ZERO4; }
;     const bool stager = (tid & 7) < 4; const int sc_ = tid >> 3, sm_ = tid & 3, scg = 64 * ctile + sc_; const bool svalid = scg < 127;
;     v4u xr1 = {0u, 0u, 0u, 0u}, xr2 = {0u, 0u, 0u, 0u}; f32x4 cs[2], sn[2], ps1[2], ps2[2]; bf16x8 bcur[2][2], bnxt[2][2];
;     ...
;     CMP_LOADA(0); CMP_LOADB(bcur, 0);
.LBB0_469:
	s_and_b64 vcc, exec, s[0:1]
	s_cbranch_vccz .LBB0_322
	s_and_b32 s61, s60, 1
	v_mov_b32_e32 v118, v232
	s_lshl_b32 s0, s61, 3
	s_load_dwordx2 s[0:1], s[12:13], s0 offset:0xa8
	v_ashrrev_i32_e32 v97, 3, v118
	v_and_b32_e32 v0, 4, v118
	v_and_b32_e32 v33, 3, v118
	s_movk_i32 s42, 0x7e
	s_waitcnt lgkmcnt(0)
	s_add_u32 s54, s0, s52
	s_addc_u32 s55, s1, s53
	s_cmp_eq_u32 s61, 0
	s_cselect_b64 s[40:41], -1, 0
	s_and_b64 s[0:1], s[40:41], exec
	s_movk_i32 s0, 0xa30
	s_cselect_b32 s45, s0, 0xab0
	s_lshl_b32 s0, s60, 5
	s_and_b32 s33, s0, 64
	v_add_u32_e32 v32, s33, v97
	s_movk_i32 s0, 0x7f
	v_cmp_eq_u32_e64 s[2:3], 0, v0
	v_cmp_ne_u32_e64 s[4:5], 0, v0
	v_cmp_gt_i32_e64 s[0:1], s0, v32
	v_cmp_lt_i32_e32 vcc, s42, v32
	v_lshlrev_b32_e32 v192, 3, v33
	s_and_saveexec_b64 s[42:43], s[4:5]
	s_xor_b64 s[42:43], exec, s[42:43]
	v_lshlrev_b32_e32 v192, 3, v33
	s_or_saveexec_b64 s[56:57], s[42:43]
	s_ashr_i32 s42, s60, 2
	s_lshl_b32 s43, s42, 6
	v_mov_b32_e32 v2, v193
	v_mov_b32_e32 v3, v193
	s_and_b32 s43, s43, 64
	v_mov_b32_e32 v0, v193
	v_mov_b32_e32 v1, v193
	v_mov_b64_e32 v[6:7], v[2:3]
	s_ashr_i32 s44, s60, 3
	s_or_b32 s43, s45, s43
	v_mov_b64_e32 v[4:5], v[0:1]
	s_xor_b64 exec, exec, s[56:57]
	s_cbranch_execz .LBB0_479
	s_and_saveexec_b64 s[58:59], vcc
	s_xor_b64 s[58:59], exec, s[58:59]
	v_lshlrev_b32_e32 v192, 3, v33
	s_or_saveexec_b64 s[58:59], s[58:59]
	v_mov_b32_e32 v4, v193
	v_mov_b32_e32 v5, v193
	v_mov_b32_e32 v6, v193
	v_mov_b32_e32 v7, v193
	v_mov_b64_e32 v[0:1], v[4:5]
	v_mov_b64_e32 v[2:3], v[6:7]
	s_xor_b64 exec, exec, s[58:59]
	s_cbranch_execz .LBB0_478
	v_lshlrev_b32_e32 v0, 4, v32
	s_ashr_i32 s45, s44, 31
	s_lshl_b64 s[66:67], s[44:45], 11
	v_ashrrev_i32_e32 v1, 31, v0
	v_lshl_add_u64 v[0:1], s[66:67], 0, v[0:1]
	v_mov_b64_e32 v[2:3], s[16:17]
	s_movk_i32 s45, 0x1c00
	v_mad_u64_u32 v[2:3], s[66:67], v0, s45, v[2:3]
	v_mad_i32_i24 v3, v1, s45, v3
	s_lshl_b32 s90, s43, 1
	v_lshl_add_u64 v[0:1], v[2:3], 0, s[90:91]
	v_lshlrev_b32_e32 v2, 4, v33
	v_mov_b32_e32 v3, v193
	v_lshl_add_u64 v[4:5], v[0:1], 0, v[2:3]
	global_load_dwordx4 v[0:3], v[4:5], off
	s_nop 0
	global_load_dwordx4 v[4:7], v[4:5], off offset:64
	s_andn2_b64 vcc, exec, s[40:41]
	s_cbranch_vccnz .LBB0_478
	v_lshlrev_b32_e32 v8, 9, v32
	v_ashrrev_i32_e32 v9, 31, v8
	v_lshlrev_b64 v[8:9], 2, v[8:9]
	v_lshl_add_u64 v[10:11], s[18:19], 0, v[8:9]
	v_lshlrev_b32_e32 v12, 2, v192
	v_mov_b32_e32 v13, v193
	v_lshl_add_u64 v[8:9], s[20:21], 0, v[8:9]
	v_lshl_add_u64 v[14:15], v[10:11], 0, v[12:13]
	v_lshl_add_u64 v[20:21], v[8:9], 0, v[12:13]
	global_load_dwordx4 v[8:11], v[14:15], off offset:16
	global_load_dwordx4 v[16:19], v[14:15], off
	s_nop 0
	global_load_dwordx4 v[12:15], v[20:21], off offset:16
	s_nop 0
	global_load_dwordx4 v[20:23], v[20:21], off

; #define LAS __attribute__((address_space(3)))
; DI f32x16 mma32(bf16x8 a, bf16x8 b, f32x16 c) { return __builtin_amdgcn_mfma_f32_32x32x16_bf16(a, b, c, 0, 0, 0); }
; DI int crow(int i, int hf) { return (i & 3) + 8 * (i >> 2) + 4 * hf; }
; DI void nsa_item(KA a, LAS unsigned char* lds, const int it) {
;     ...
;         of[0] = ot[0] * g0; of[1] = ot[1] * g0;
;     ...
;     float m_ref = 0.f, l_run = 0.f; f32x16 ot[2] = {ZERO16, ZERO16}; int curtype = 0;
;     for (int i = 0; i < n; ++i) {
;         const int desc = LIST[i]; const int ty = desc >> 8, j = desc & 255;
;         const LAS bf16* Kc = (i & 1) ? Kt1 : Kt; const LAS bf16* Vc = (i & 1) ? VT1 : VT;
;         if (ty != curtype) { const float lt = l_run + __shfl_xor(l_run, 32); const float sc = g1 / lt; of[0] += ot[0] * sc; of[1] += ot[1] * sc; ot[0] = ZERO16; ot[1] = ZERO16; m_ref = 0.f; l_run = 0.f; curtype = ty; }
;         const bool rowoff = (ty == 0) && (((mysel >> j) & 1u) == 0u);
;         const int mode = (j == qb) ? 1 : ((ty == 1 && j == qb - 8) ? 2 : 0);
;         const float init = rowoff ? -INFINITY : -m_ref;
;         f32x16 st[2];
; #pragma unroll
;         for (int i2 = 0; i2 < 16; ++i2) { st[0][i2] = init; st[1][i2] = init; }
; #pragma unroll
;         for (int kt = 0; kt < 2; ++kt)
; #pragma unroll
;             for (int s = 0; s < 4; ++s) { const bf16x8 af = *(const LAS bf16x8*)(Kc + (32 * kt + r) * PA + 16 * s + 8 * hf); st[kt] = mma32(af, bq[s], st[kt]); }
;         if (mode != 0) {
; #pragma unroll
;             for (int kt = 0; kt < 2; ++kt)
; #pragma unroll
;                 for (int i2 = 0; i2 < 16; ++i2) { const int kl = 32 * kt + crow(i2, hf); const bool bad = rowoff || (mode == 1 && kl > tql) || (mode == 2 && kl <= tql); st[kt][i2] = bad ? -INFINITY : st[kt][i2]; }
.LBB0_794:
	v_add_f32_e32 v33, 1.0, v33
	v_rcp_f32_e32 v34, v33
	s_andn2_b64 vcc, exec, s[0:1]
	v_readlane_b32 s90, v254, 47
	v_pk_mul_f32 v[124:125], v[34:35], v[30:31] op_sel_hi:[0,1]
	v_pk_mul_f32 v[120:121], v[34:35], v[28:29] op_sel_hi:[0,1]
	v_pk_mul_f32 v[116:117], v[34:35], v[26:27] op_sel_hi:[0,1]
	v_pk_mul_f32 v[112:113], v[34:35], v[24:25] op_sel_hi:[0,1]
	v_pk_mul_f32 v[108:109], v[34:35], v[22:23] op_sel_hi:[0,1]
	v_pk_mul_f32 v[104:105], v[34:35], v[20:21] op_sel_hi:[0,1]
	v_pk_mul_f32 v[100:101], v[34:35], v[18:19] op_sel_hi:[0,1]
	v_pk_mul_f32 v[96:97], v[34:35], v[16:17] op_sel_hi:[0,1]
	v_pk_mul_f32 v[122:123], v[34:35], v[14:15] op_sel_hi:[0,1]
	v_pk_mul_f32 v[118:119], v[34:35], v[12:13] op_sel_hi:[0,1]
	v_pk_mul_f32 v[114:115], v[34:35], v[10:11] op_sel_hi:[0,1]
	v_pk_mul_f32 v[110:111], v[34:35], v[8:9] op_sel_hi:[0,1]
	v_pk_mul_f32 v[106:107], v[34:35], v[6:7] op_sel_hi:[0,1]
	v_pk_mul_f32 v[102:103], v[34:35], v[4:5] op_sel_hi:[0,1]
	v_pk_mul_f32 v[98:99], v[34:35], v[2:3] op_sel_hi:[0,1]
	v_pk_mul_f32 v[94:95], v[34:35], v[0:1] op_sel_hi:[0,1]
	v_mov_b32_e32 v31, 0
	s_cbranch_vccnz .LBB0_811
	v_cmp_gt_u32_e64 s[0:1], v92, v135
	v_or_b32_e32 v0, 2, v92
	s_sub_i32 s85, 23, s40
	v_writelane_b32 v254, s0, 49
	s_mov_b32 s87, 0
	s_mov_b32 s88, 0
	v_writelane_b32 v254, s1, 50
	v_cmp_le_u32_e64 s[0:1], v92, v135
	v_mov_b32_e32 v137, 0
	v_mov_b32_e32 v16, 0
	v_writelane_b32 v254, s0, 51
	s_nop 1
	v_writelane_b32 v254, s1, 52
	v_cmp_ge_u32_e64 s[0:1], v92, v135
	s_nop 1
	v_writelane_b32 v254, s0, 53
	s_nop 1
	v_writelane_b32 v254, s1, 54
	v_cmp_lt_u32_e64 s[0:1], v92, v135
	s_nop 1
	v_writelane_b32 v254, s0, 55
	s_nop 1
	v_writelane_b32 v254, s1, 56
	v_cmp_gt_u32_e64 s[0:1], v0, v135
	s_nop 1
	v_writelane_b32 v254, s0, 57
	s_nop 1
	v_writelane_b32 v254, s1, 58
	v_cmp_le_u32_e64 s[0:1], v0, v135
	v_or_b32_e32 v0, 3, v92
	s_nop 0
	v_writelane_b32 v254, s0, 59
	s_nop 1
	v_writelane_b32 v254, s1, 60
	v_cmp_gt_u32_e64 s[0:1], v0, v135
	s_nop 1
	v_writelane_b32 v254, s0, 61
	s_nop 1
	v_writelane_b32 v254, s1, 62
	v_cmp_le_u32_e64 s[0:1], v0, v135
	v_or_b32_e32 v0, 8, v92
	s_nop 0
	v_writelane_b32 v254, s0, 63
	s_nop 0
	v_readlane_b32 s86, v254, 13
	v_writelane_b32 v245, s1, 0
	v_cmp_gt_u32_e64 s[0:1], v0, v135
	s_nop 1
	v_writelane_b32 v245, s0, 1
	s_nop 1
	v_writelane_b32 v245, s1, 2
	v_cmp_le_u32_e64 s[0:1], v0, v135
	v_or_b32_e32 v0, 9, v92
	s_nop 0
	v_writelane_b32 v245, s0, 3
	s_nop 1
	v_writelane_b32 v245, s1, 4
	v_cmp_gt_u32_e64 s[0:1], v0, v135
	s_nop 1
	v_writelane_b32 v245, s0, 5
	s_nop 1
	v_writelane_b32 v245, s1, 6
	v_cmp_le_u32_e64 s[0:1], v0, v135
	v_or_b32_e32 v0, 10, v92
	s_nop 0
	v_writelane_b32 v245, s0, 7
	s_nop 1
	v_writelane_b32 v245, s1, 8
	v_cmp_gt_u32_e64 s[0:1], v0, v135
	s_nop 1
	v_writelane_b32 v245, s0, 9
	s_nop 1
	v_writelane_b32 v245, s1, 10
	v_cmp_le_u32_e64 s[0:1], v0, v135
	v_or_b32_e32 v0, 11, v92
	s_nop 0
	v_writelane_b32 v245, s0, 11
	s_nop 1
	v_writelane_b32 v245, s1, 12
	v_cmp_gt_u32_e64 s[0:1], v0, v135
	s_nop 1
	v_writelane_b32 v245, s0, 13
	s_nop 1
	v_writelane_b32 v245, s1, 14
	v_cmp_le_u32_e64 s[0:1], v0, v135
	v_or_b32_e32 v0, 16, v92
	s_nop 0
	v_writelane_b32 v245, s0, 15
	s_nop 1
	v_writelane_b32 v245, s1, 16
	v_cmp_gt_u32_e64 s[0:1], v0, v135
	s_nop 1
	v_writelane_b32 v245, s0, 17
	s_nop 1
	v_writelane_b32 v245, s1, 18
	v_cmp_le_u32_e64 s[0:1], v0, v135
	v_or_b32_e32 v0, 17, v92
	s_nop 0
	v_writelane_b32 v245, s0, 19
	s_nop 1
	v_writelane_b32 v245, s1, 20
	v_cmp_gt_u32_e64 s[0:1], v0, v135
	s_nop 1
	v_writelane_b32 v245, s0, 21
	s_nop 1
	v_writelane_b32 v245, s1, 22
	v_cmp_le_u32_e64 s[0:1], v0, v135
	v_or_b32_e32 v0, 18, v92
	s_nop 0
	v_writelane_b32 v245, s0, 23
	s_nop 1
	v_writelane_b32 v245, s1, 24
	v_cmp_gt_u32_e64 s[0:1], v0, v135
	s_nop 1
	v_writelane_b32 v245, s0, 25
	s_nop 1
	v_writelane_b32 v245, s1, 26
	v_cmp_le_u32_e64 s[0:1], v0, v135
	v_or_b32_e32 v0, 19, v92
	s_nop 0
	v_writelane_b32 v245, s0, 27
	s_nop 1
	v_writelane_b32 v245, s1, 28
	v_cmp_gt_u32_e64 s[0:1], v0, v135
	s_nop 1
	v_writelane_b32 v245, s0, 29
	s_nop 1
	v_writelane_b32 v245, s1, 30
	v_cmp_le_u32_e64 s[0:1], v0, v135
	v_or_b32_e32 v0, 24, v92
	s_nop 0
	v_writelane_b32 v245, s0, 31
	s_nop 1
	v_writelane_b32 v245, s1, 32
	v_cmp_gt_u32_e64 s[0:1], v0, v135
	s_nop 1
	v_writelane_b32 v245, s0, 33
	s_nop 1
	v_writelane_b32 v245, s1, 34
	v_cmp_le_u32_e64 s[0:1], v0, v135
	v_or_b32_e32 v0, 25, v92
	v_cmp_gt_u32_e64 s[92:93], v0, v135
	v_cmp_le_u32_e64 s[94:95], v0, v135
	v_or_b32_e32 v0, 26, v92
	v_cmp_gt_u32_e64 s[96:97], v0, v135
	v_cmp_le_u32_e64 s[6:7], v0, v135
	v_or_b32_e32 v0, 27, v92
	v_cmp_gt_u32_e64 s[8:9], v0, v135
	v_cmp_le_u32_e64 s[10:11], v0, v135
	v_or_b32_e32 v0, 32, v92
	v_cmp_gt_u32_e64 s[12:13], v0, v135
	v_cmp_le_u32_e64 s[14:15], v0, v135
	v_or_b32_e32 v0, 33, v92
	v_cmp_gt_u32_e64 s[16:17], v0, v135
	v_cmp_le_u32_e64 s[18:19], v0, v135
	v_or_b32_e32 v0, 34, v92
	v_cmp_gt_u32_e64 s[20:21], v0, v135
	v_cmp_le_u32_e64 s[22:23], v0, v135
	v_or_b32_e32 v0, 35, v92
	v_cmp_gt_u32_e64 s[24:25], v0, v135
	v_cmp_le_u32_e64 s[26:27], v0, v135
	v_or_b32_e32 v0, 40, v92
	v_cmp_gt_u32_e64 s[28:29], v0, v135
	v_cmp_le_u32_e64 s[30:31], v0, v135
	v_or_b32_e32 v0, 41, v92
	v_cmp_gt_u32_e64 s[34:35], v0, v135
	v_cmp_le_u32_e64 s[36:37], v0, v135
	v_or_b32_e32 v0, 42, v92
	v_cmp_gt_u32_e64 s[38:39], v0, v135
	v_cmp_le_u32_e64 s[4:5], v0, v135
	v_or_b32_e32 v0, 43, v92
	v_writelane_b32 v245, s0, 35
	v_cmp_gt_u32_e64 s[40:41], v0, v135
	v_cmp_le_u32_e64 s[2:3], v0, v135
	v_or_b32_e32 v0, 48, v92
	v_writelane_b32 v245, s1, 36
	v_cmp_gt_u32_e64 s[0:1], v0, v135
	v_cmp_le_u32_e64 s[42:43], v0, v135
; #define LAS __attribute__((address_space(3)))
; DI f32x16 mma32(bf16x8 a, bf16x8 b, f32x16 c) { return __builtin_amdgcn_mfma_f32_32x32x16_bf16(a, b, c, 0, 0, 0); }
; DI void nsa_item(KA a, LAS unsigned char* lds, const int it) {
;     ...
;     float m_ref = 0.f, l_run = 0.f; f32x16 ot[2] = {ZERO16, ZERO16}; int curtype = 0;
;     for (int i = 0; i < n; ++i) {
;         const int desc = LIST[i]; const int ty = desc >> 8, j = desc & 255;
;         const LAS bf16* Kc = (i & 1) ? Kt1 : Kt; const LAS bf16* Vc = (i & 1) ? VT1 : VT;
;         if (ty != curtype) { const float lt = l_run + __shfl_xor(l_run, 32); const float sc = g1 / lt; of[0] += ot[0] * sc; of[1] += ot[1] * sc; ot[0] = ZERO16; ot[1] = ZERO16; m_ref = 0.f; l_run = 0.f; curtype = ty; }
;         const bool rowoff = (ty == 0) && (((mysel >> j) & 1u) == 0u);
;         const int mode = (j == qb) ? 1 : ((ty == 1 && j == qb - 8) ? 2 : 0);
;         const float init = rowoff ? -INFINITY : -m_ref;
;         f32x16 st[2];
; #pragma unroll
;         for (int i2 = 0; i2 < 16; ++i2) { st[0][i2] = init; st[1][i2] = init; }
; #pragma unroll
;         for (int kt = 0; kt < 2; ++kt)
; #pragma unroll
;             for (int s = 0; s < 4; ++s) { const bf16x8 af = *(const LAS bf16x8*)(Kc + (32 * kt + r) * PA + 16 * s + 8 * hf); st[kt] = mma32(af, bq[s], st[kt]); }
	v_or_b32_e32 v0, 49, v92
	v_cmp_gt_u32_e64 s[44:45], v0, v135
	v_cmp_le_u32_e64 s[46:47], v0, v135
	v_or_b32_e32 v0, 50, v92
	v_cmp_gt_u32_e64 s[48:49], v0, v135
	v_cmp_le_u32_e64 s[50:51], v0, v135
	v_or_b32_e32 v0, 51, v92
	v_cmp_gt_u32_e64 s[52:53], v0, v135
	v_cmp_le_u32_e64 s[54:55], v0, v135
	v_or_b32_e32 v0, 56, v92
	v_cmp_gt_u32_e64 s[56:57], v0, v135
	v_cmp_le_u32_e64 s[58:59], v0, v135
	v_or_b32_e32 v0, 57, v92
	v_cmp_gt_u32_e64 s[60:61], v0, v135
	v_cmp_le_u32_e64 s[62:63], v0, v135
	v_or_b32_e32 v0, 58, v92
	v_cmp_gt_u32_e64 s[64:65], v0, v135
	v_cmp_le_u32_e64 s[66:67], v0, v135
	v_or_b32_e32 v0, 59, v92
	v_cmp_gt_u32_e64 s[68:69], v0, v135
	v_cmp_le_u32_e64 s[70:71], v0, v135
	v_mov_b32_e32 v135, 0
	v_mov_b32_e32 v0, 0
	v_mov_b32_e32 v1, v135
	v_mov_b32_e32 v2, v135
	v_mov_b32_e32 v3, v135
	v_mov_b32_e32 v4, v135
	v_mov_b32_e32 v5, v135
	v_mov_b32_e32 v6, v135
	v_mov_b32_e32 v7, v135
	v_mov_b32_e32 v8, v135
	v_mov_b32_e32 v9, v135
	v_mov_b32_e32 v10, v135
	v_mov_b32_e32 v11, v135
	v_mov_b32_e32 v12, v135
	v_mov_b32_e32 v13, v135
	v_mov_b32_e32 v14, v135
	v_mov_b32_e32 v15, v135
	v_mov_b32_e32 v17, v135
	v_mov_b32_e32 v18, v135
	v_mov_b32_e32 v19, v135
	v_mov_b32_e32 v20, v135
	v_mov_b32_e32 v21, v135
	v_mov_b32_e32 v22, v135
	v_mov_b32_e32 v23, v135
	v_mov_b32_e32 v24, v135
	v_mov_b32_e32 v25, v135
	v_mov_b32_e32 v26, v135
	v_mov_b32_e32 v27, v135
	v_mov_b32_e32 v28, v135
	v_mov_b32_e32 v29, v135
	v_mov_b32_e32 v30, v135
	v_mov_b32_e32 v31, v135
	s_add_i32 s74, s86, -8
	v_mov_b32_e32 v191, s74
	ds_read_b32 v191, v191
	v_add3_u32 v231, 0, v90, v130
	s_movk_i32 s74, 0x4800
	v_add3_u32 v230, s74, v90, v131
	s_waitcnt lgkmcnt(0)
	s_branch .Lnsa_H
.LBB0_796:
	ds_read_b128 v[144:147], v231
	ds_read_b128 v[148:151], v231 offset:32
	ds_read_b128 v[170:173], v231 offset:64
	ds_read_b128 v[174:177], v231 offset:96
	ds_read_b128 v[178:181], v231 offset:4608
	ds_read_b128 v[182:185], v231 offset:4640
	ds_read_b128 v[186:189], v231 offset:4672
	ds_read_b128 v[206:209], v231 offset:4704
	ds_read_b128 v[210:213], v230
	ds_read_b128 v[218:221], v230 offset:8704
	ds_read_b128 v[222:225], v230 offset:8736
	ds_read_b128 v[214:217], v230 offset:32
	ds_read_b128 v[226:229], v230 offset:64
	ds_read_b128 v[152:155], v230 offset:8768
	ds_read_b128 v[246:249], v230 offset:96
	s_add_i32 s89, s86, -4
	v_mov_b32_e32 v191, s89
	ds_read_b32 v191, v191
	s_waitcnt lgkmcnt(15)
	v_mfma_f32_32x32x16_bf16 v[48:63], v[144:147], v[72:75], v[32:47]
	s_cmp_eq_u32 s83, s85
	s_cselect_b64 vcc, -1, 0
	s_cmp_eq_u32 s82, 1
	s_cselect_b64 s[82:83], -1, 0
	s_and_b64 s[82:83], s[82:83], vcc
	s_or_b64 vcc, s[80:81], s[82:83]
	s_andn2_b64 vcc, exec, vcc
	s_waitcnt lgkmcnt(14)
	v_mfma_f32_32x32x16_bf16 v[48:63], v[148:151], v[64:67], v[48:63]
	s_waitcnt lgkmcnt(13)
	v_mfma_f32_32x32x16_bf16 v[48:63], v[170:173], v[68:71], v[48:63]
	s_waitcnt lgkmcnt(12)
	v_mfma_f32_32x32x16_bf16 v[48:63], v[174:177], v[76:79], v[48:63]
	s_waitcnt lgkmcnt(11)
	v_mfma_f32_32x32x16_bf16 v[32:47], v[178:181], v[72:75], v[32:47]
	s_waitcnt lgkmcnt(10)
	v_mfma_f32_32x32x16_bf16 v[32:47], v[182:185], v[64:67], v[32:47]
	s_waitcnt lgkmcnt(9)
	v_mfma_f32_32x32x16_bf16 v[32:47], v[186:189], v[68:71], v[32:47]
	s_waitcnt lgkmcnt(8)
	v_mfma_f32_32x32x16_bf16 v[32:47], v[206:209], v[76:79], v[32:47]
	ds_read_b128 v[148:151], v230 offset:8800
	s_cbranch_vccnz .LBB0_800
	s_xor_b64 vcc, s[80:81], -1
	s_and_b64 s[82:83], vcc, s[82:83]
	v_readlane_b32 vcc_lo, v254, 49
	v_readlane_b32 vcc_hi, v254, 50
	s_mov_b32 s89, s91
	v_readlane_b32 s90, v254, 51
	s_and_b64 vcc, s[80:81], vcc
	v_readlane_b32 s91, v254, 52
	s_or_b64 vcc, s[78:79], vcc
	s_and_b64 s[90:91], s[82:83], s[90:91]
	s_or_b64 vcc, vcc, s[90:91]
	v_readlane_b32 s90, v254, 53
	v_cndmask_b32_e32 v48, v48, v240, vcc
	v_readlane_b32 s91, v254, 54
	v_readlane_b32 vcc_lo, v254, 55
	s_and_b64 s[90:91], s[80:81], s[90:91]
	v_readlane_b32 vcc_hi, v254, 56
	s_or_b64 s[90:91], s[78:79], s[90:91]
	s_and_b64 vcc, s[82:83], vcc
	s_or_b64 vcc, s[90:91], vcc
	v_readlane_b32 s90, v254, 57
	v_cndmask_b32_e32 v49, v49, v240, vcc
	v_readlane_b32 s91, v254, 58
	v_readlane_b32 vcc_lo, v254, 59
	s_and_b64 s[90:91], s[80:81], s[90:91]
	v_readlane_b32 vcc_hi, v254, 60
	s_or_b64 s[90:91], s[78:79], s[90:91]
	s_and_b64 vcc, s[82:83], vcc
	s_or_b64 vcc, s[90:91], vcc
	v_readlane_b32 s90, v254, 61
	v_cndmask_b32_e32 v50, v50, v240, vcc
	v_readlane_b32 s91, v254, 62
	v_readlane_b32 vcc_lo, v254, 63
	s_and_b64 s[90:91], s[80:81], s[90:91]
	v_readlane_b32 vcc_hi, v245, 0
	s_or_b64 s[90:91], s[78:79], s[90:91]
	s_and_b64 vcc, s[82:83], vcc
	s_or_b64 vcc, s[90:91], vcc
	v_readlane_b32 s90, v245, 1
	v_cndmask_b32_e32 v51, v51, v240, vcc
	v_readlane_b32 s91, v245, 2
	v_readlane_b32 vcc_lo, v245, 3
	s_and_b64 s[90:91], s[80:81], s[90:91]
	v_readlane_b32 vcc_hi, v245, 4
	s_or_b64 s[90:91], s[78:79], s[90:91]
	s_and_b64 vcc, s[82:83], vcc
	s_or_b64 vcc, s[90:91], vcc
	v_readlane_b32 s90, v245, 5
	v_cndmask_b32_e32 v52, v52, v240, vcc
	v_readlane_b32 s91, v245, 6
	v_readlane_b32 vcc_lo, v245, 7
	s_and_b64 s[90:91], s[80:81], s[90:91]
	v_readlane_b32 vcc_hi, v245, 8
	s_or_b64 s[90:91], s[78:79], s[90:91]
	s_and_b64 vcc, s[82:83], vcc
	s_or_b64 vcc, s[90:91], vcc
	v_readlane_b32 s90, v245, 9
	v_cndmask_b32_e32 v53, v53, v240, vcc
	v_readlane_b32 s91, v245, 10
	v_readlane_b32 vcc_lo, v245, 11
	s_and_b64 s[90:91], s[80:81], s[90:91]
	v_readlane_b32 vcc_hi, v245, 12
	s_or_b64 s[90:91], s[78:79], s[90:91]
; DI int crow(int i, int hf) { return (i & 3) + 8 * (i >> 2) + 4 * hf; }
; DI void nsa_item(KA a, LAS unsigned char* lds, const int it) {
;     ...
;         if (mode != 0) {
; #pragma unroll
;             for (int kt = 0; kt < 2; ++kt)
; #pragma unroll
;                 for (int i2 = 0; i2 < 16; ++i2) { const int kl = 32 * kt + crow(i2, hf); const bool bad = rowoff || (mode == 1 && kl > tql) || (mode == 2 && kl <= tql); st[kt][i2] = bad ? -INFINITY : st[kt][i2]; }
;         }
	s_and_b64 vcc, s[82:83], vcc
	s_or_b64 vcc, s[90:91], vcc
	v_readlane_b32 s90, v245, 13
	v_cndmask_b32_e32 v54, v54, v240, vcc
	v_readlane_b32 s91, v245, 14
	v_readlane_b32 vcc_lo, v245, 15
	s_and_b64 s[90:91], s[80:81], s[90:91]
	v_readlane_b32 vcc_hi, v245, 16
	s_or_b64 s[90:91], s[78:79], s[90:91]
	s_and_b64 vcc, s[82:83], vcc
	s_or_b64 vcc, s[90:91], vcc
	v_readlane_b32 s90, v245, 17
	v_cndmask_b32_e32 v55, v55, v240, vcc
	v_readlane_b32 s91, v245, 18
	v_readlane_b32 vcc_lo, v245, 19
	s_and_b64 s[90:91], s[80:81], s[90:91]
	v_readlane_b32 vcc_hi, v245, 20
	s_or_b64 s[90:91], s[78:79], s[90:91]
	s_and_b64 vcc, s[82:83], vcc
	s_or_b64 vcc, s[90:91], vcc
	v_readlane_b32 s90, v245, 21
	v_cndmask_b32_e32 v56, v56, v240, vcc
	v_readlane_b32 s91, v245, 22
	v_readlane_b32 vcc_lo, v245, 23
	s_and_b64 s[90:91], s[80:81], s[90:91]
	v_readlane_b32 vcc_hi, v245, 24
	s_or_b64 s[90:91], s[78:79], s[90:91]
	s_and_b64 vcc, s[82:83], vcc
	s_or_b64 vcc, s[90:91], vcc
	v_readlane_b32 s90, v245, 25
	v_cndmask_b32_e32 v57, v57, v240, vcc
	v_readlane_b32 s91, v245, 26
	v_readlane_b32 vcc_lo, v245, 27
	s_and_b64 s[90:91], s[80:81], s[90:91]
	v_readlane_b32 vcc_hi, v245, 28
	s_or_b64 s[90:91], s[78:79], s[90:91]
	s_and_b64 vcc, s[82:83], vcc
	s_or_b64 vcc, s[90:91], vcc
	v_readlane_b32 s90, v245, 29
	v_cndmask_b32_e32 v58, v58, v240, vcc
	v_readlane_b32 s91, v245, 30
	v_readlane_b32 vcc_lo, v245, 31
	s_and_b64 s[90:91], s[80:81], s[90:91]
	v_readlane_b32 vcc_hi, v245, 32
	s_or_b64 s[90:91], s[78:79], s[90:91]
	s_and_b64 vcc, s[82:83], vcc
	s_or_b64 vcc, s[90:91], vcc
	v_readlane_b32 s90, v245, 33
	v_cndmask_b32_e32 v59, v59, v240, vcc
	v_readlane_b32 s91, v245, 34
	v_readlane_b32 vcc_lo, v245, 35
	s_and_b64 s[90:91], s[80:81], s[90:91]
	v_readlane_b32 vcc_hi, v245, 36
	s_or_b64 s[90:91], s[78:79], s[90:91]
	s_and_b64 vcc, s[82:83], vcc
	s_or_b64 vcc, s[90:91], vcc
	s_and_b64 s[90:91], s[80:81], s[92:93]
	v_cndmask_b32_e32 v60, v60, v240, vcc
	s_or_b64 s[90:91], s[78:79], s[90:91]
	s_and_b64 vcc, s[82:83], s[94:95]
	s_or_b64 vcc, s[90:91], vcc
	s_and_b64 s[90:91], s[80:81], s[96:97]
	v_cndmask_b32_e32 v61, v61, v240, vcc
	s_or_b64 s[90:91], s[78:79], s[90:91]
	s_and_b64 vcc, s[82:83], s[6:7]
	s_or_b64 vcc, s[90:91], vcc
	s_and_b64 s[90:91], s[80:81], s[8:9]
	v_cndmask_b32_e32 v62, v62, v240, vcc
	s_or_b64 s[90:91], s[78:79], s[90:91]
	s_and_b64 vcc, s[82:83], s[10:11]
	s_or_b64 vcc, s[90:91], vcc
	s_and_b64 s[90:91], s[80:81], s[12:13]
	v_cndmask_b32_e32 v63, v63, v240, vcc
	s_or_b64 s[90:91], s[78:79], s[90:91]
	s_and_b64 vcc, s[82:83], s[14:15]
	s_or_b64 vcc, s[90:91], vcc
	s_and_b64 s[90:91], s[80:81], s[16:17]
	v_cndmask_b32_e32 v32, v32, v240, vcc
	s_or_b64 s[90:91], s[78:79], s[90:91]
	s_and_b64 vcc, s[82:83], s[18:19]
	s_or_b64 vcc, s[90:91], vcc
	s_and_b64 s[90:91], s[80:81], s[20:21]
	v_cndmask_b32_e32 v33, v33, v240, vcc
	s_or_b64 s[90:91], s[78:79], s[90:91]
	s_and_b64 vcc, s[82:83], s[22:23]
	s_or_b64 vcc, s[90:91], vcc
	s_and_b64 s[90:91], s[80:81], s[24:25]
	v_cndmask_b32_e32 v34, v34, v240, vcc
	s_or_b64 s[90:91], s[78:79], s[90:91]
	s_and_b64 vcc, s[82:83], s[26:27]
	s_or_b64 vcc, s[90:91], vcc
	s_and_b64 s[90:91], s[80:81], s[28:29]
	v_cndmask_b32_e32 v35, v35, v240, vcc
	s_or_b64 s[90:91], s[78:79], s[90:91]
	s_and_b64 vcc, s[82:83], s[30:31]
	s_or_b64 vcc, s[90:91], vcc
	s_and_b64 s[90:91], s[80:81], s[34:35]
	v_cndmask_b32_e32 v36, v36, v240, vcc
	s_or_b64 s[90:91], s[78:79], s[90:91]
	s_and_b64 vcc, s[82:83], s[36:37]
	s_or_b64 vcc, s[90:91], vcc
	s_and_b64 s[90:91], s[80:81], s[38:39]
	v_cndmask_b32_e32 v37, v37, v240, vcc
	s_or_b64 s[90:91], s[78:79], s[90:91]
	s_and_b64 vcc, s[82:83], s[4:5]
	s_or_b64 vcc, s[90:91], vcc
	s_and_b64 s[90:91], s[80:81], s[40:41]
	v_cndmask_b32_e32 v38, v38, v240, vcc
	s_or_b64 s[90:91], s[78:79], s[90:91]
	s_and_b64 vcc, s[82:83], s[2:3]
	s_or_b64 vcc, s[90:91], vcc
	s_and_b64 s[90:91], s[80:81], s[0:1]
	v_cndmask_b32_e32 v39, v39, v240, vcc
	s_or_b64 s[90:91], s[78:79], s[90:91]
	s_and_b64 vcc, s[82:83], s[42:43]
	s_or_b64 vcc, s[90:91], vcc
	s_and_b64 s[90:91], s[80:81], s[44:45]
	v_cndmask_b32_e32 v40, v40, v240, vcc
	s_or_b64 s[90:91], s[78:79], s[90:91]
	s_and_b64 vcc, s[82:83], s[46:47]
	s_or_b64 vcc, s[90:91], vcc
	s_and_b64 s[90:91], s[80:81], s[48:49]
	v_cndmask_b32_e32 v41, v41, v240, vcc
	s_or_b64 s[90:91], s[78:79], s[90:91]
	s_and_b64 vcc, s[82:83], s[50:51]
	s_or_b64 vcc, s[90:91], vcc
	s_and_b64 s[90:91], s[80:81], s[52:53]
	v_cndmask_b32_e32 v42, v42, v240, vcc
	s_or_b64 s[90:91], s[78:79], s[90:91]
	s_and_b64 vcc, s[82:83], s[54:55]
	s_or_b64 vcc, s[90:91], vcc
	s_and_b64 s[90:91], s[80:81], s[56:57]
	v_cndmask_b32_e32 v43, v43, v240, vcc
	s_or_b64 s[90:91], s[78:79], s[90:91]
	s_and_b64 vcc, s[82:83], s[58:59]
	s_or_b64 vcc, s[90:91], vcc
	s_and_b64 s[90:91], s[80:81], s[60:61]
	v_cndmask_b32_e32 v44, v44, v240, vcc
	s_or_b64 s[90:91], s[78:79], s[90:91]
	s_and_b64 vcc, s[82:83], s[62:63]
	s_or_b64 vcc, s[90:91], vcc
	s_and_b64 s[90:91], s[80:81], s[64:65]
	v_cndmask_b32_e32 v45, v45, v240, vcc
	s_or_b64 s[90:91], s[78:79], s[90:91]
	s_and_b64 vcc, s[82:83], s[66:67]
	s_and_b64 s[80:81], s[80:81], s[68:69]
	s_or_b64 vcc, s[90:91], vcc
	s_or_b64 s[78:79], s[78:79], s[80:81]
	s_and_b64 s[80:81], s[82:83], s[70:71]
	v_cndmask_b32_e32 v46, v46, v240, vcc
	s_or_b64 vcc, s[78:79], s[80:81]
	v_readlane_b32 s90, v254, 47
	s_mov_b32 s91, s89
	v_cndmask_b32_e32 v47, v47, v240, vcc

; #define LAS __attribute__((address_space(3)))
; DI f32x16 mma32(bf16x8 a, bf16x8 b, f32x16 c) { return __builtin_amdgcn_mfma_f32_32x32x16_bf16(a, b, c, 0, 0, 0); }
; DI bf16x8 packp(const f32x16& x, const int h8) { v4u p; p.x = pk2(x[h8 + 0], x[h8 + 1]); p.y = pk2(x[h8 + 2], x[h8 + 3]); p.z = pk2(x[h8 + 4], x[h8 + 5]); p.w = pk2(x[h8 + 6], x[h8 + 7]); return __builtin_bit_cast(bf16x8, p); }
; #define NSA_STORE(Kb, Vb) do { *(LAS v4u*)((Kb) + skey * PA + 8 * sch) = kreg; LAS unsigned* d0_ = (LAS unsigned*)((Vb) + (4 * sdg) * PV + vpos(2 * skp)); \
;         d0_[0] = (vr0.x & 0xffffu) | (vr1.x << 16); d0_[PV / 2] = (vr0.x >> 16) | (vr1.x & 0xffff0000u); d0_[PV] = (vr0.y & 0xffffu) | (vr1.y << 16); d0_[3 * PV / 2] = (vr0.y >> 16) | (vr1.y & 0xffff0000u); } while (0)
; DI void nsa_item(KA a, LAS unsigned char* lds, const int it) {
;     ...
;     for (int i = 0; i < n; ++i) {
;         const int desc = LIST[i]; const int ty = desc >> 8, j = desc & 255;
;         const LAS bf16* Kc = (i & 1) ? Kt1 : Kt; const LAS bf16* Vc = (i & 1) ? VT1 : VT;
;         if (ty != curtype) { const float lt = l_run + __shfl_xor(l_run, 32); const float sc = g1 / lt; of[0] += ot[0] * sc; of[1] += ot[1] * sc; ot[0] = ZERO16; ot[1] = ZERO16; m_ref = 0.f; l_run = 0.f; curtype = ty; }
;         const bool rowoff = (ty == 0) && (((mysel >> j) & 1u) == 0u);
;         const int mode = (j == qb) ? 1 : ((ty == 1 && j == qb - 8) ? 2 : 0);
;         const float init = rowoff ? -INFINITY : -m_ref;
;         f32x16 st[2];
; #pragma unroll
;         for (int i2 = 0; i2 < 16; ++i2) { st[0][i2] = init; st[1][i2] = init; }
;     ...
;             for (int i2 = 0; i2 < 16; i2 += 2) { const float p0 = __builtin_amdgcn_exp2f(st[kt][i2]), p1 = __builtin_amdgcn_exp2f(st[kt][i2 + 1]); st[kt][i2] = p0; st[kt][i2 + 1] = p1; ls2 += (f32x2){p0, p1}; }
;         l_run += ls2[0] + ls2[1];
; #pragma unroll
;         for (int sp = 0; sp < 4; ++sp) { const bf16x8 pf = packp(st[sp >> 1], 8 * (sp & 1));
; #pragma unroll
;             for (int dh = 0; dh < 2; ++dh) ot[dh] = mma32(vfrag(Vc, 32 * dh + r, sp, hf), pf, ot[dh]); }
;         if (i + 1 < n) { if (i & 1) NSA_STORE(Kt, VT); else NSA_STORE(Kt1, VT1); if (i + 2 < n) NSA_LOAD(LIST[i + 2]); }
;         __syncthreads();
.LBB0_807:
	s_add_i32 s86, s86, 4
	s_bitcmp1_b32 s76, 0
	s_cselect_b32 s74, 0x9000, 0
	s_movk_i32 s75, 0x4800
	s_cselect_b32 s75, 0xb400, s75
	v_add3_u32 v231, s74, v90, v130
	v_add3_u32 v230, s75, v90, v131
	v_pk_add_f32 v[48:49], v[48:49], v[50:51]
	v_pk_add_f32 v[52:53], v[52:53], v[54:55]
	v_pk_add_f32 v[56:57], v[56:57], v[58:59]
	v_pk_add_f32 v[60:61], v[60:61], v[62:63]
	v_pk_add_f32 v[32:33], v[32:33], v[34:35]
	v_pk_add_f32 v[36:37], v[36:37], v[38:39]
	v_pk_add_f32 v[40:41], v[40:41], v[42:43]
	v_pk_add_f32 v[44:45], v[44:45], v[46:47]
	v_pk_add_f32 v[48:49], v[48:49], v[52:53]
	v_pk_add_f32 v[56:57], v[56:57], v[60:61]
	v_pk_add_f32 v[32:33], v[32:33], v[36:37]
	v_pk_add_f32 v[40:41], v[40:41], v[44:45]
	v_pk_add_f32 v[48:49], v[48:49], v[56:57]
	v_pk_add_f32 v[32:33], v[32:33], v[40:41]
	s_nop 0
	v_pk_add_f32 v[32:33], v[32:33], v[48:49]
	s_nop 0
	v_add_f32_e32 v32, v32, v33
	v_add_f32_e32 v135, v135, v32
	s_cmp_lg_u32 s84, s76
	s_cbranch_scc0 .Lnsa_exitbar
	s_mov_b32 s87, s76
.Lnsa_H:
	v_readfirstlane_b32 s78, v191
	s_ashr_i32 s82, s78, 8
	s_cmp_eq_u32 s82, s88
	s_cbranch_scc1 .LBB0_798
	ds_bpermute_b32 v32, v134, v135
	v_mov_b32_e32 v137, 0
	s_mov_b32 s88, s82
	s_waitcnt lgkmcnt(0)
	v_add_f32_e32 v32, v135, v32
	v_div_scale_f32 v33, s[74:75], v32, v32, v93
	v_rcp_f32_e32 v34, v33
	v_div_scale_f32 v35, vcc, v93, v32, v93
	v_mov_b32_e32 v135, 0
	v_fma_f32 v36, -v33, v34, 1.0
	v_fmac_f32_e32 v34, v36, v34
	v_mul_f32_e32 v36, v35, v34
	v_fma_f32 v37, -v33, v36, v35
	v_fmac_f32_e32 v36, v37, v34
	v_fma_f32 v33, -v33, v36, v35
	v_div_fmas_f32 v33, v33, v34, v36
	v_div_fixup_f32 v32, v33, v32, v93
	v_pk_fma_f32 v[124:125], v[30:31], v[32:33], v[124:125] op_sel_hi:[1,0,1]
	v_pk_fma_f32 v[120:121], v[28:29], v[32:33], v[120:121] op_sel_hi:[1,0,1]
	v_pk_fma_f32 v[116:117], v[26:27], v[32:33], v[116:117] op_sel_hi:[1,0,1]
	v_pk_fma_f32 v[112:113], v[24:25], v[32:33], v[112:113] op_sel_hi:[1,0,1]
	v_pk_fma_f32 v[108:109], v[22:23], v[32:33], v[108:109] op_sel_hi:[1,0,1]
	v_pk_fma_f32 v[104:105], v[20:21], v[32:33], v[104:105] op_sel_hi:[1,0,1]
	v_pk_fma_f32 v[100:101], v[18:19], v[32:33], v[100:101] op_sel_hi:[1,0,1]
	v_pk_fma_f32 v[96:97], v[16:17], v[32:33], v[96:97] op_sel_hi:[1,0,1]
	v_pk_fma_f32 v[122:123], v[14:15], v[32:33], v[122:123] op_sel_hi:[1,0,1]
	v_pk_fma_f32 v[118:119], v[12:13], v[32:33], v[118:119] op_sel_hi:[1,0,1]
	v_pk_fma_f32 v[114:115], v[10:11], v[32:33], v[114:115] op_sel_hi:[1,0,1]
	v_pk_fma_f32 v[110:111], v[8:9], v[32:33], v[110:111] op_sel_hi:[1,0,1]
	v_pk_fma_f32 v[106:107], v[6:7], v[32:33], v[106:107] op_sel_hi:[1,0,1]
	v_pk_fma_f32 v[102:103], v[4:5], v[32:33], v[102:103] op_sel_hi:[1,0,1]
	v_pk_fma_f32 v[98:99], v[2:3], v[32:33], v[98:99] op_sel_hi:[1,0,1]
	v_pk_fma_f32 v[94:95], v[0:1], v[32:33], v[94:95] op_sel_hi:[1,0,1]
	v_mov_b32_e32 v0, 0
	v_mov_b32_e32 v1, v137
	v_mov_b32_e32 v2, v137
	v_mov_b32_e32 v3, v137
	v_mov_b32_e32 v4, v137
	v_mov_b32_e32 v5, v137
	v_mov_b32_e32 v6, v137
	v_mov_b32_e32 v7, v137
	v_mov_b32_e32 v8, v137
	v_mov_b32_e32 v9, v137
	v_mov_b32_e32 v10, v137
	v_mov_b32_e32 v11, v137
	v_mov_b32_e32 v12, v137
	v_mov_b32_e32 v13, v137
	v_mov_b32_e32 v14, v137
	v_mov_b32_e32 v15, v137
	v_mov_b32_e32 v16, 0
	v_mov_b32_e32 v17, v137
	v_mov_b32_e32 v18, v137
	v_mov_b32_e32 v19, v137
	v_mov_b32_e32 v20, v137
	v_mov_b32_e32 v21, v137
	v_mov_b32_e32 v22, v137
	v_mov_b32_e32 v23, v137
	v_mov_b32_e32 v24, v137
	v_mov_b32_e32 v25, v137
	v_mov_b32_e32 v26, v137
	v_mov_b32_e32 v27, v137
	v_mov_b32_e32 v28, v137
	v_mov_b32_e32 v29, v137
	v_mov_b32_e32 v30, v137
	v_mov_b32_e32 v31, v137
.LBB0_798:
	s_and_b32 s83, s78, 0xff
	s_and_b32 s76, s87, 1
	s_bitcmp1_b32 s87, 0
	s_cselect_b64 s[74:75], -1, 0
	s_cmp_eq_u32 s76, 0
	s_cselect_b64 s[76:77], -1, 0
	s_and_b64 s[80:81], s[76:77], exec
	v_readlane_b32 s79, v254, 14
	s_cselect_b32 s89, 0, s79
	v_add3_u32 v89, s89, v90, v130
	s_cmpk_lt_u32 s78, 0x100
	s_cselect_b64 s[80:81], -1, 0
	s_lshl_b32 s78, 1, s78
	v_and_b32_e32 v32, s78, v141
	v_cmp_eq_u32_e32 vcc, 0, v32
	s_and_b64 s[78:79], s[80:81], vcc
	v_cndmask_b32_e64 v32, -v137, v240, s[78:79]
	v_mov_b32_e32 v33, v32
	v_mov_b32_e32 v34, v32
	v_mov_b32_e32 v35, v32
	v_mov_b32_e32 v36, v32
	v_mov_b32_e32 v37, v32
	v_mov_b32_e32 v38, v32
	v_mov_b32_e32 v39, v32
	v_mov_b32_e32 v40, v32
	v_mov_b32_e32 v41, v32
	v_mov_b32_e32 v42, v32
	v_mov_b32_e32 v43, v32
	v_mov_b32_e32 v44, v32
	v_mov_b32_e32 v45, v32
	v_mov_b32_e32 v46, v32
	v_mov_b32_e32 v47, v32
	s_cmp_eq_u32 s83, s90
	s_cselect_b64 s[80:81], -1, 0
	s_waitcnt lgkmcnt(0)
	s_barrier
	s_branch .LBB0_796
.Lnsa_exitbar:
	s_waitcnt lgkmcnt(0)
	s_barrier
	s_branch .LBB0_600
